# diff block v3: second V-fragment register set read a stage ahead, 4 K-fragment groups, merged counted LDS waits (6 per block instead of 16)
# speedup vs baseline: 1.0202x; 1.0033x over previous
; #define LAS __attribute__((address_space(3)))
; #define MFMA32(a, b, c) __builtin_amdgcn_mfma_f32_32x32x16_bf16((a), (b), (c), 0, 0, 0)
; DI float fexp2(float x) { return __builtin_amdgcn_exp2f(x); }
; DI f32x16 zero16() { f32x16 z; for (int i = 0; i < 16; ++i) z[i] = 0.f; return z; }
; template <int MODE>
; DI void dense256_unit(const Params& p, int l, int b, int nq, int hd, LAS unsigned char* lds) {
;     ...
;       for (int mt = 0; mt < 2; ++mt) {
;         LAS unsigned char* krow = kt + (32 * mt + r) * W_RS + (8 * h) * 2;
;         const bf16x8 a0 = *(const LAS bf16x8*)(krow), a1 = *(const LAS bf16x8*)(krow + 32), a2 = *(const LAS bf16x8*)(krow + 64), a3 = *(const LAS bf16x8*)(krow + 96);
;         if (MODE == 0) {
;           f32x16 s1 = zero16(), s2 = zero16();
;           s1 = MFMA32(a0, qf[0], s1); s1 = MFMA32(a1, qf[1], s1); s2 = MFMA32(a2, qf[2], s2); s2 = MFMA32(a3, qf[3], s2);
; #pragma unroll
;           for (int i = 0; i < 16; ++i) { s1[i] = fexp2(s1[i]); l1 += s1[i]; s2[i] = fexp2(s2[i]); l2 += s2[i]; }
; #pragma unroll
;           for (int s = 0; s < 2; ++s) {
;             const bf16x8 p1 = pack8(s1, s), p2 = pack8(s2, s);
; #pragma unroll
;             for (int et = 0; et < 2; ++et) { const bf16x8 vf = vfrag144(vt, 32 * mt + 16 * s + 4 * h, 32 * et, lane); o1[et] = MFMA32(vf, p1, o1[et]); o2[et] = MFMA32(vf, p2, o2[et]); }
;           }
.LBB0_973:
	s_cmp_eq_u32 s13, 0
	s_cbranch_scc0 .Lmy_diff_buf1
	ds_read_b128 v[208:211], v192
	ds_read_b128 v[212:215], v192 offset:32
	ds_read_b128 v[216:219], v192 offset:64
	ds_read_b128 v[220:223], v192 offset:96
	s_waitcnt lgkmcnt(2)
	v_mfma_f32_32x32x16_bf16 v[66:81], v[208:211], v[114:117], 0
	v_mfma_f32_32x32x16_bf16 v[66:81], v[212:215], v[106:109], v[66:81]
	ds_read_b128 v[208:211], v192 offset:4608
	ds_read_b128 v[212:215], v192 offset:4640
	s_nop 10
	s_waitcnt lgkmcnt(2)
	v_mfma_f32_32x32x16_bf16 v[82:97], v[216:219], v[110:113], 0
	v_exp_f32_e32 v66, v66
	v_exp_f32_e32 v67, v67
	v_exp_f32_e32 v68, v68
	v_exp_f32_e32 v69, v69
	v_exp_f32_e32 v70, v70
	v_exp_f32_e32 v71, v71
	v_exp_f32_e32 v72, v72
	v_exp_f32_e32 v73, v73
	v_add_f32_e32 v151, v151, v66
	v_add_f32_e32 v151, v151, v67
	v_add_f32_e32 v151, v151, v68
	v_add_f32_e32 v151, v151, v69
	v_exp_f32_e32 v74, v74
	v_exp_f32_e32 v75, v75
	v_exp_f32_e32 v76, v76
	v_exp_f32_e32 v77, v77
	v_exp_f32_e32 v78, v78
	v_exp_f32_e32 v79, v79
	v_exp_f32_e32 v80, v80
	v_exp_f32_e32 v81, v81
	v_mfma_f32_32x32x16_bf16 v[82:97], v[220:223], v[118:121], v[82:97]
	ds_read_b128 v[216:219], v192 offset:4672
	ds_read_b128 v[220:223], v192 offset:4704
	ds_read_b64_tr_b16 v[164:165], v193 offset:18432
	ds_read_b64_tr_b16 v[166:167], v193 offset:19584
	ds_read_b64_tr_b16 v[124:125], v193 offset:18496
	ds_read_b64_tr_b16 v[126:127], v193 offset:19648
	ds_read_b64_tr_b16 v[156:157], v193 offset:20736
	ds_read_b64_tr_b16 v[158:159], v193 offset:21888
	ds_read_b64_tr_b16 v[160:161], v193 offset:20800
	ds_read_b64_tr_b16 v[162:163], v193 offset:21952
	v_add_f32_e32 v151, v151, v70
	v_add_f32_e32 v151, v151, v71
	v_add_f32_e32 v151, v151, v72
	v_add_f32_e32 v151, v151, v73
	v_add_f32_e32 v151, v151, v74
	v_add_f32_e32 v151, v151, v75
	v_add_f32_e32 v151, v151, v76
	v_add_f32_e32 v151, v151, v77
	v_add_f32_e32 v151, v151, v78
	v_add_f32_e32 v151, v151, v79
	v_add_f32_e32 v151, v151, v80
	v_add_f32_e32 v151, v151, v81
	v_cvt_pk_bf16_f32 v138, v66, v67
	v_cvt_pk_bf16_f32 v139, v68, v69
	v_cvt_pk_bf16_f32 v140, v70, v71
	v_cvt_pk_bf16_f32 v141, v72, v73
	v_cvt_pk_bf16_f32 v142, v74, v75
	v_cvt_pk_bf16_f32 v143, v76, v77
	v_cvt_pk_bf16_f32 v144, v78, v79
	v_cvt_pk_bf16_f32 v145, v80, v81
	s_waitcnt lgkmcnt(10)
	v_mfma_f32_32x32x16_bf16 v[66:81], v[208:211], v[114:117], 0
	v_exp_f32_e32 v82, v82
	v_exp_f32_e32 v83, v83
	v_exp_f32_e32 v84, v84
	v_exp_f32_e32 v85, v85
	v_exp_f32_e32 v86, v86
	v_exp_f32_e32 v87, v87
	v_mfma_f32_32x32x16_bf16 v[66:81], v[212:215], v[106:109], v[66:81]
	v_exp_f32_e32 v88, v88
	v_exp_f32_e32 v89, v89
	v_add_f32_e32 v150, v150, v82
	v_add_f32_e32 v150, v150, v83
	v_add_f32_e32 v150, v150, v84
	v_add_f32_e32 v150, v150, v85
	s_waitcnt lgkmcnt(0)
	v_mfma_f32_32x32x16_bf16 v[34:49], v[164:167], v[138:141], v[34:49]
	v_exp_f32_e32 v90, v90
	v_exp_f32_e32 v91, v91
	v_exp_f32_e32 v92, v92
	v_exp_f32_e32 v93, v93
	v_exp_f32_e32 v94, v94
	v_exp_f32_e32 v95, v95
	v_mfma_f32_32x32x16_bf16 v[2:17], v[124:127], v[138:141], v[2:17]
	v_exp_f32_e32 v96, v96
	v_exp_f32_e32 v97, v97
	v_add_f32_e32 v150, v150, v86
	v_add_f32_e32 v150, v150, v87
	v_add_f32_e32 v150, v150, v88
	v_add_f32_e32 v150, v150, v89
	v_mfma_f32_32x32x16_bf16 v[34:49], v[156:159], v[142:145], v[34:49]
	v_add_f32_e32 v150, v150, v90
	v_add_f32_e32 v150, v150, v91
	v_add_f32_e32 v150, v150, v92
	v_add_f32_e32 v150, v150, v93
	v_add_f32_e32 v150, v150, v94
	v_add_f32_e32 v150, v150, v95
	v_mfma_f32_32x32x16_bf16 v[2:17], v[160:163], v[142:145], v[2:17]
	ds_read_b64_tr_b16 v[224:225], v193 offset:23040
	ds_read_b64_tr_b16 v[226:227], v193 offset:24192
	ds_read_b64_tr_b16 v[228:229], v193 offset:23104
	ds_read_b64_tr_b16 v[230:231], v193 offset:24256
	ds_read_b64_tr_b16 v[232:233], v193 offset:25344
	ds_read_b64_tr_b16 v[234:235], v193 offset:26496
	ds_read_b64_tr_b16 v[236:237], v193 offset:25408
	ds_read_b64_tr_b16 v[238:239], v193 offset:26560
	v_add_f32_e32 v150, v150, v96
	v_add_f32_e32 v150, v150, v97
	v_cvt_pk_bf16_f32 v146, v82, v83
	v_cvt_pk_bf16_f32 v147, v84, v85
	v_cvt_pk_bf16_f32 v148, v86, v87
	v_cvt_pk_bf16_f32 v149, v88, v89
	v_cvt_pk_bf16_f32 v152, v90, v91
	v_cvt_pk_bf16_f32 v153, v92, v93
	v_cvt_pk_bf16_f32 v154, v94, v95
	v_cvt_pk_bf16_f32 v155, v96, v97
	v_mfma_f32_32x32x16_bf16 v[82:97], v[216:219], v[110:113], 0
	v_exp_f32_e32 v66, v66
	v_exp_f32_e32 v67, v67
	v_exp_f32_e32 v68, v68
	v_exp_f32_e32 v69, v69
	v_exp_f32_e32 v70, v70
	v_exp_f32_e32 v71, v71
	v_mfma_f32_32x32x16_bf16 v[82:97], v[220:223], v[118:121], v[82:97]
	v_exp_f32_e32 v72, v72
	v_exp_f32_e32 v73, v73
	v_add_f32_e32 v151, v151, v66
	v_add_f32_e32 v151, v151, v67
	v_add_f32_e32 v151, v151, v68
	v_add_f32_e32 v151, v151, v69
	v_mfma_f32_32x32x16_bf16 v[50:65], v[164:167], v[146:149], v[50:65]
	v_exp_f32_e32 v74, v74
	v_exp_f32_e32 v75, v75
	v_exp_f32_e32 v76, v76
	v_exp_f32_e32 v77, v77
	v_exp_f32_e32 v78, v78
	v_exp_f32_e32 v79, v79
	v_mfma_f32_32x32x16_bf16 v[18:33], v[124:127], v[146:149], v[18:33]
	v_exp_f32_e32 v80, v80
	v_exp_f32_e32 v81, v81
	v_add_f32_e32 v151, v151, v70
	v_add_f32_e32 v151, v151, v71
	v_add_f32_e32 v151, v151, v72
	v_add_f32_e32 v151, v151, v73
	v_mfma_f32_32x32x16_bf16 v[50:65], v[156:159], v[152:155], v[50:65]
	v_add_f32_e32 v151, v151, v74
	v_add_f32_e32 v151, v151, v75
	v_add_f32_e32 v151, v151, v76
	v_add_f32_e32 v151, v151, v77
	v_add_f32_e32 v151, v151, v78
	v_add_f32_e32 v151, v151, v79
	v_mfma_f32_32x32x16_bf16 v[18:33], v[160:163], v[152:155], v[18:33]
	v_add_f32_e32 v151, v151, v80
	v_add_f32_e32 v151, v151, v81
	v_cvt_pk_bf16_f32 v138, v66, v67
	v_cvt_pk_bf16_f32 v139, v68, v69
	v_cvt_pk_bf16_f32 v140, v70, v71
	v_cvt_pk_bf16_f32 v141, v72, v73
	v_cvt_pk_bf16_f32 v142, v74, v75
	v_cvt_pk_bf16_f32 v143, v76, v77
	v_cvt_pk_bf16_f32 v144, v78, v79
	v_cvt_pk_bf16_f32 v145, v80, v81
	s_waitcnt lgkmcnt(0)
; #define LAS __attribute__((address_space(3)))
; #define MFMA32(a, b, c) __builtin_amdgcn_mfma_f32_32x32x16_bf16((a), (b), (c), 0, 0, 0)
; DI float fexp2(float x) { return __builtin_amdgcn_exp2f(x); }
; DI f32x16 zero16() { f32x16 z; for (int i = 0; i < 16; ++i) z[i] = 0.f; return z; }
; template <int MODE>
; DI void dense256_unit(const Params& p, int l, int b, int nq, int hd, LAS unsigned char* lds) {
;     ...
;       for (int mt = 0; mt < 2; ++mt) {
;         LAS unsigned char* krow = kt + (32 * mt + r) * W_RS + (8 * h) * 2;
;         const bf16x8 a0 = *(const LAS bf16x8*)(krow), a1 = *(const LAS bf16x8*)(krow + 32), a2 = *(const LAS bf16x8*)(krow + 64), a3 = *(const LAS bf16x8*)(krow + 96);
;         if (MODE == 0) {
;           f32x16 s1 = zero16(), s2 = zero16();
;           s1 = MFMA32(a0, qf[0], s1); s1 = MFMA32(a1, qf[1], s1); s2 = MFMA32(a2, qf[2], s2); s2 = MFMA32(a3, qf[3], s2);
; #pragma unroll
;           for (int i = 0; i < 16; ++i) { s1[i] = fexp2(s1[i]); l1 += s1[i]; s2[i] = fexp2(s2[i]); l2 += s2[i]; }
; #pragma unroll
;           for (int s = 0; s < 2; ++s) {
;             const bf16x8 p1 = pack8(s1, s), p2 = pack8(s2, s);
; #pragma unroll
;             for (int et = 0; et < 2; ++et) { const bf16x8 vf = vfrag144(vt, 32 * mt + 16 * s + 4 * h, 32 * et, lane); o1[et] = MFMA32(vf, p1, o1[et]); o2[et] = MFMA32(vf, p2, o2[et]); }
;           }
	v_mfma_f32_32x32x16_bf16 v[34:49], v[224:227], v[138:141], v[34:49]
	v_exp_f32_e32 v82, v82
	v_exp_f32_e32 v83, v83
	v_exp_f32_e32 v84, v84
	v_exp_f32_e32 v85, v85
	v_exp_f32_e32 v86, v86
	v_exp_f32_e32 v87, v87
	v_exp_f32_e32 v88, v88
	v_exp_f32_e32 v89, v89
	v_add_f32_e32 v150, v150, v82
	v_add_f32_e32 v150, v150, v83
	v_mfma_f32_32x32x16_bf16 v[2:17], v[228:231], v[138:141], v[2:17]
	v_add_f32_e32 v150, v150, v84
	v_add_f32_e32 v150, v150, v85
	v_exp_f32_e32 v90, v90
	v_exp_f32_e32 v91, v91
	v_exp_f32_e32 v92, v92
	v_exp_f32_e32 v93, v93
	v_exp_f32_e32 v94, v94
	v_exp_f32_e32 v95, v95
	v_exp_f32_e32 v96, v96
	v_exp_f32_e32 v97, v97
	v_mfma_f32_32x32x16_bf16 v[34:49], v[232:235], v[142:145], v[34:49]
	v_add_f32_e32 v150, v150, v86
	v_add_f32_e32 v150, v150, v87
	v_add_f32_e32 v150, v150, v88
	v_add_f32_e32 v150, v150, v89
	v_add_f32_e32 v150, v150, v90
	v_add_f32_e32 v150, v150, v91
	v_add_f32_e32 v150, v150, v92
	v_add_f32_e32 v150, v150, v93
	v_add_f32_e32 v150, v150, v94
	v_add_f32_e32 v150, v150, v95
	v_mfma_f32_32x32x16_bf16 v[2:17], v[236:239], v[142:145], v[2:17]
	v_add_f32_e32 v150, v150, v96
	v_add_f32_e32 v150, v150, v97
	v_cvt_pk_bf16_f32 v146, v82, v83
	v_cvt_pk_bf16_f32 v147, v84, v85
	v_cvt_pk_bf16_f32 v148, v86, v87
	v_cvt_pk_bf16_f32 v149, v88, v89
	v_cvt_pk_bf16_f32 v152, v90, v91
	v_cvt_pk_bf16_f32 v153, v92, v93
	v_cvt_pk_bf16_f32 v154, v94, v95
	v_cvt_pk_bf16_f32 v155, v96, v97
	v_mfma_f32_32x32x16_bf16 v[50:65], v[224:227], v[146:149], v[50:65]
	v_mfma_f32_32x32x16_bf16 v[18:33], v[228:231], v[146:149], v[18:33]
	v_mfma_f32_32x32x16_bf16 v[50:65], v[232:235], v[152:155], v[50:65]
	v_mfma_f32_32x32x16_bf16 v[18:33], v[236:239], v[152:155], v[18:33]
	s_branch .Lmy_diff_done
.Lmy_diff_buf1:
	ds_read_b128 v[208:211], v192 offset:9216
	ds_read_b128 v[212:215], v192 offset:9248
	ds_read_b128 v[216:219], v192 offset:9280
	ds_read_b128 v[220:223], v192 offset:9312
	s_waitcnt lgkmcnt(2)
	v_mfma_f32_32x32x16_bf16 v[66:81], v[208:211], v[114:117], 0
	v_mfma_f32_32x32x16_bf16 v[66:81], v[212:215], v[106:109], v[66:81]
	ds_read_b128 v[208:211], v192 offset:13824
	ds_read_b128 v[212:215], v192 offset:13856
	s_nop 10
	s_waitcnt lgkmcnt(2)
	v_mfma_f32_32x32x16_bf16 v[82:97], v[216:219], v[110:113], 0
	v_exp_f32_e32 v66, v66
	v_exp_f32_e32 v67, v67
	v_exp_f32_e32 v68, v68
	v_exp_f32_e32 v69, v69
	v_exp_f32_e32 v70, v70
	v_exp_f32_e32 v71, v71
	v_exp_f32_e32 v72, v72
	v_exp_f32_e32 v73, v73
	v_add_f32_e32 v151, v151, v66
	v_add_f32_e32 v151, v151, v67
	v_add_f32_e32 v151, v151, v68
	v_add_f32_e32 v151, v151, v69
	v_exp_f32_e32 v74, v74
	v_exp_f32_e32 v75, v75
	v_exp_f32_e32 v76, v76
	v_exp_f32_e32 v77, v77
	v_exp_f32_e32 v78, v78
	v_exp_f32_e32 v79, v79
	v_exp_f32_e32 v80, v80
	v_exp_f32_e32 v81, v81
	v_mfma_f32_32x32x16_bf16 v[82:97], v[220:223], v[118:121], v[82:97]
	ds_read_b128 v[216:219], v192 offset:13888
	ds_read_b128 v[220:223], v192 offset:13920
	ds_read_b64_tr_b16 v[164:165], v193 offset:27648
	ds_read_b64_tr_b16 v[166:167], v193 offset:28800
	ds_read_b64_tr_b16 v[124:125], v193 offset:27712
	ds_read_b64_tr_b16 v[126:127], v193 offset:28864
	ds_read_b64_tr_b16 v[156:157], v193 offset:29952
	ds_read_b64_tr_b16 v[158:159], v193 offset:31104
	ds_read_b64_tr_b16 v[160:161], v193 offset:30016
	ds_read_b64_tr_b16 v[162:163], v193 offset:31168
	v_add_f32_e32 v151, v151, v70
	v_add_f32_e32 v151, v151, v71
	v_add_f32_e32 v151, v151, v72
	v_add_f32_e32 v151, v151, v73
	v_add_f32_e32 v151, v151, v74
	v_add_f32_e32 v151, v151, v75
	v_add_f32_e32 v151, v151, v76
	v_add_f32_e32 v151, v151, v77
	v_add_f32_e32 v151, v151, v78
	v_add_f32_e32 v151, v151, v79
	v_add_f32_e32 v151, v151, v80
	v_add_f32_e32 v151, v151, v81
	v_cvt_pk_bf16_f32 v138, v66, v67
	v_cvt_pk_bf16_f32 v139, v68, v69
	v_cvt_pk_bf16_f32 v140, v70, v71
	v_cvt_pk_bf16_f32 v141, v72, v73
	v_cvt_pk_bf16_f32 v142, v74, v75
	v_cvt_pk_bf16_f32 v143, v76, v77
	v_cvt_pk_bf16_f32 v144, v78, v79
	v_cvt_pk_bf16_f32 v145, v80, v81
	s_waitcnt lgkmcnt(10)
	v_mfma_f32_32x32x16_bf16 v[66:81], v[208:211], v[114:117], 0
	v_exp_f32_e32 v82, v82
	v_exp_f32_e32 v83, v83
	v_exp_f32_e32 v84, v84
	v_exp_f32_e32 v85, v85
	v_exp_f32_e32 v86, v86
	v_exp_f32_e32 v87, v87
	v_mfma_f32_32x32x16_bf16 v[66:81], v[212:215], v[106:109], v[66:81]
	v_exp_f32_e32 v88, v88
	v_exp_f32_e32 v89, v89
	v_add_f32_e32 v150, v150, v82
	v_add_f32_e32 v150, v150, v83
	v_add_f32_e32 v150, v150, v84
	v_add_f32_e32 v150, v150, v85
	s_waitcnt lgkmcnt(0)
; #define LAS __attribute__((address_space(3)))
; #define MFMA32(a, b, c) __builtin_amdgcn_mfma_f32_32x32x16_bf16((a), (b), (c), 0, 0, 0)
; DI float fexp2(float x) { return __builtin_amdgcn_exp2f(x); }
; DI f32x16 zero16() { f32x16 z; for (int i = 0; i < 16; ++i) z[i] = 0.f; return z; }
; template <int MODE>
; DI void dense256_unit(const Params& p, int l, int b, int nq, int hd, LAS unsigned char* lds) {
;     ...
;       for (int mt = 0; mt < 2; ++mt) {
;         LAS unsigned char* krow = kt + (32 * mt + r) * W_RS + (8 * h) * 2;
;         const bf16x8 a0 = *(const LAS bf16x8*)(krow), a1 = *(const LAS bf16x8*)(krow + 32), a2 = *(const LAS bf16x8*)(krow + 64), a3 = *(const LAS bf16x8*)(krow + 96);
;         if (MODE == 0) {
;           f32x16 s1 = zero16(), s2 = zero16();
;           s1 = MFMA32(a0, qf[0], s1); s1 = MFMA32(a1, qf[1], s1); s2 = MFMA32(a2, qf[2], s2); s2 = MFMA32(a3, qf[3], s2);
; #pragma unroll
;           for (int i = 0; i < 16; ++i) { s1[i] = fexp2(s1[i]); l1 += s1[i]; s2[i] = fexp2(s2[i]); l2 += s2[i]; }
; #pragma unroll
;           for (int s = 0; s < 2; ++s) {
;             const bf16x8 p1 = pack8(s1, s), p2 = pack8(s2, s);
; #pragma unroll
;             for (int et = 0; et < 2; ++et) { const bf16x8 vf = vfrag144(vt, 32 * mt + 16 * s + 4 * h, 32 * et, lane); o1[et] = MFMA32(vf, p1, o1[et]); o2[et] = MFMA32(vf, p2, o2[et]); }
;           }
	v_mfma_f32_32x32x16_bf16 v[34:49], v[164:167], v[138:141], v[34:49]
	v_exp_f32_e32 v90, v90
	v_exp_f32_e32 v91, v91
	v_exp_f32_e32 v92, v92
	v_exp_f32_e32 v93, v93
	v_exp_f32_e32 v94, v94
	v_exp_f32_e32 v95, v95
	v_mfma_f32_32x32x16_bf16 v[2:17], v[124:127], v[138:141], v[2:17]
	v_exp_f32_e32 v96, v96
	v_exp_f32_e32 v97, v97
	v_add_f32_e32 v150, v150, v86
	v_add_f32_e32 v150, v150, v87
	v_add_f32_e32 v150, v150, v88
	v_add_f32_e32 v150, v150, v89
	v_mfma_f32_32x32x16_bf16 v[34:49], v[156:159], v[142:145], v[34:49]
	v_add_f32_e32 v150, v150, v90
	v_add_f32_e32 v150, v150, v91
	v_add_f32_e32 v150, v150, v92
	v_add_f32_e32 v150, v150, v93
	v_add_f32_e32 v150, v150, v94
	v_add_f32_e32 v150, v150, v95
	v_mfma_f32_32x32x16_bf16 v[2:17], v[160:163], v[142:145], v[2:17]
	ds_read_b64_tr_b16 v[224:225], v193 offset:32256
	ds_read_b64_tr_b16 v[226:227], v193 offset:33408
	ds_read_b64_tr_b16 v[228:229], v193 offset:32320
	ds_read_b64_tr_b16 v[230:231], v193 offset:33472
	ds_read_b64_tr_b16 v[232:233], v193 offset:34560
	ds_read_b64_tr_b16 v[234:235], v193 offset:35712
	ds_read_b64_tr_b16 v[236:237], v193 offset:34624
	ds_read_b64_tr_b16 v[238:239], v193 offset:35776
	v_add_f32_e32 v150, v150, v96
	v_add_f32_e32 v150, v150, v97
	v_cvt_pk_bf16_f32 v146, v82, v83
	v_cvt_pk_bf16_f32 v147, v84, v85
	v_cvt_pk_bf16_f32 v148, v86, v87
	v_cvt_pk_bf16_f32 v149, v88, v89
	v_cvt_pk_bf16_f32 v152, v90, v91
	v_cvt_pk_bf16_f32 v153, v92, v93
	v_cvt_pk_bf16_f32 v154, v94, v95
	v_cvt_pk_bf16_f32 v155, v96, v97
	v_mfma_f32_32x32x16_bf16 v[82:97], v[216:219], v[110:113], 0
	v_exp_f32_e32 v66, v66
	v_exp_f32_e32 v67, v67
	v_exp_f32_e32 v68, v68
	v_exp_f32_e32 v69, v69
	v_exp_f32_e32 v70, v70
	v_exp_f32_e32 v71, v71
	v_mfma_f32_32x32x16_bf16 v[82:97], v[220:223], v[118:121], v[82:97]
	v_exp_f32_e32 v72, v72
	v_exp_f32_e32 v73, v73
	v_add_f32_e32 v151, v151, v66
	v_add_f32_e32 v151, v151, v67
	v_add_f32_e32 v151, v151, v68
	v_add_f32_e32 v151, v151, v69
	v_mfma_f32_32x32x16_bf16 v[50:65], v[164:167], v[146:149], v[50:65]
	v_exp_f32_e32 v74, v74
	v_exp_f32_e32 v75, v75
	v_exp_f32_e32 v76, v76
	v_exp_f32_e32 v77, v77
	v_exp_f32_e32 v78, v78
	v_exp_f32_e32 v79, v79
	v_mfma_f32_32x32x16_bf16 v[18:33], v[124:127], v[146:149], v[18:33]
	v_exp_f32_e32 v80, v80
	v_exp_f32_e32 v81, v81
	v_add_f32_e32 v151, v151, v70
	v_add_f32_e32 v151, v151, v71
	v_add_f32_e32 v151, v151, v72
	v_add_f32_e32 v151, v151, v73
	v_mfma_f32_32x32x16_bf16 v[50:65], v[156:159], v[152:155], v[50:65]
	v_add_f32_e32 v151, v151, v74
	v_add_f32_e32 v151, v151, v75
	v_add_f32_e32 v151, v151, v76
	v_add_f32_e32 v151, v151, v77
	v_add_f32_e32 v151, v151, v78
	v_add_f32_e32 v151, v151, v79
	v_mfma_f32_32x32x16_bf16 v[18:33], v[160:163], v[152:155], v[18:33]
	v_add_f32_e32 v151, v151, v80
	v_add_f32_e32 v151, v151, v81
	v_cvt_pk_bf16_f32 v138, v66, v67
	v_cvt_pk_bf16_f32 v139, v68, v69
	v_cvt_pk_bf16_f32 v140, v70, v71
	v_cvt_pk_bf16_f32 v141, v72, v73
	v_cvt_pk_bf16_f32 v142, v74, v75
	v_cvt_pk_bf16_f32 v143, v76, v77
	v_cvt_pk_bf16_f32 v144, v78, v79
	v_cvt_pk_bf16_f32 v145, v80, v81
	s_waitcnt lgkmcnt(0)
	v_mfma_f32_32x32x16_bf16 v[34:49], v[224:227], v[138:141], v[34:49]
	v_exp_f32_e32 v82, v82
	v_exp_f32_e32 v83, v83
	v_exp_f32_e32 v84, v84
	v_exp_f32_e32 v85, v85
	v_exp_f32_e32 v86, v86
	v_exp_f32_e32 v87, v87
	v_exp_f32_e32 v88, v88
	v_exp_f32_e32 v89, v89
	v_add_f32_e32 v150, v150, v82
	v_add_f32_e32 v150, v150, v83
	v_mfma_f32_32x32x16_bf16 v[2:17], v[228:231], v[138:141], v[2:17]
	v_add_f32_e32 v150, v150, v84
	v_add_f32_e32 v150, v150, v85
	v_exp_f32_e32 v90, v90
	v_exp_f32_e32 v91, v91
	v_exp_f32_e32 v92, v92
	v_exp_f32_e32 v93, v93
	v_exp_f32_e32 v94, v94
	v_exp_f32_e32 v95, v95
	v_exp_f32_e32 v96, v96
	v_exp_f32_e32 v97, v97
	v_mfma_f32_32x32x16_bf16 v[34:49], v[232:235], v[142:145], v[34:49]
	v_add_f32_e32 v150, v150, v86
	v_add_f32_e32 v150, v150, v87
	v_add_f32_e32 v150, v150, v88
	v_add_f32_e32 v150, v150, v89
	v_add_f32_e32 v150, v150, v90
	v_add_f32_e32 v150, v150, v91
	v_add_f32_e32 v150, v150, v92
	v_add_f32_e32 v150, v150, v93
	v_add_f32_e32 v150, v150, v94
	v_add_f32_e32 v150, v150, v95
	v_mfma_f32_32x32x16_bf16 v[2:17], v[236:239], v[142:145], v[2:17]
	v_add_f32_e32 v150, v150, v96
	v_add_f32_e32 v150, v150, v97
	v_cvt_pk_bf16_f32 v146, v82, v83
	v_cvt_pk_bf16_f32 v147, v84, v85
	v_cvt_pk_bf16_f32 v148, v86, v87
	v_cvt_pk_bf16_f32 v149, v88, v89
	v_cvt_pk_bf16_f32 v152, v90, v91
	v_cvt_pk_bf16_f32 v153, v92, v93
	v_cvt_pk_bf16_f32 v154, v94, v95
	v_cvt_pk_bf16_f32 v155, v96, v97
	v_mfma_f32_32x32x16_bf16 v[50:65], v[224:227], v[146:149], v[50:65]
	v_mfma_f32_32x32x16_bf16 v[18:33], v[228:231], v[146:149], v[18:33]
	v_mfma_f32_32x32x16_bf16 v[50:65], v[232:235], v[152:155], v[50:65]
	v_mfma_f32_32x32x16_bf16 v[18:33], v[236:239], v[152:155], v[18:33]
